# attention loop: per-tile LDS-DMA issue moved from behind the barrier to the start of the second half-step; mix-GEMM K-loop peeled too
# speedup vs baseline: 1.0311x; 1.0012x over previous
.Ldyn_back:
.LBB0_310:
	s_cmp_lt_i32 s90, s82
	s_cselect_b64 s[4:5], -1, 0
	s_cmp_lt_u32 s90, 4
	s_cselect_b64 s[2:3], -1, 0
	s_mov_b64 s[12:13], -1
	s_and_b64 vcc, exec, s[2:3]
	s_cbranch_vccnz .LBB0_312
	s_waitcnt lgkmcnt(1)
	v_mfma_f32_32x32x16_bf16 v[130:145], v[158:161], v[166:169], v[2:17]
	v_cndmask_b32_e64 v114, v197, v196, s[4:5]
	v_pk_add_f32 v[128:129], v[114:115], v[16:17] op_sel_hi:[0,1]
	v_pk_add_f32 v[126:127], v[114:115], v[14:15] op_sel_hi:[0,1]
	v_pk_add_f32 v[124:125], v[114:115], v[12:13] op_sel_hi:[0,1]
	v_pk_add_f32 v[122:123], v[114:115], v[10:11] op_sel_hi:[0,1]
	v_pk_add_f32 v[120:121], v[114:115], v[8:9] op_sel_hi:[0,1]
	v_pk_add_f32 v[118:119], v[114:115], v[6:7] op_sel_hi:[0,1]
	v_pk_add_f32 v[116:117], v[114:115], v[4:5] op_sel_hi:[0,1]
	v_pk_add_f32 v[114:115], v[114:115], v[2:3] op_sel_hi:[0,1]
	s_and_b64 s[4:5], s[4:5], exec
	s_cselect_b32 s4, 0, s77
	s_sub_i32 s4, s90, s4
	s_add_i32 s4, s4, -4
	s_cmp_ge_i32 s4, s99
	s_cselect_b64 s[12:13], -1, 0
	s_not_b64 s[4:5], s[12:13]
	v_mfma_f32_32x32x16_bf16 v[114:129], v[150:153], v[166:169], v[114:129]
	v_max3_f32 v246, v98, v97, v105
	v_exp_f32_e32 v246, v246
	s_waitcnt lgkmcnt(0)
	v_mfma_f32_32x32x16_bf16 v[130:145], v[154:157], v[162:165], v[130:145]
	v_mul_f32_e32 v246, 0x4f800000, v246
	v_cmp_ge_f32_e32 vcc, v246, v175
	v_mfma_f32_32x32x16_bf16 v[114:129], v[146:149], v[162:165], v[114:129]
	s_mov_b64 s[80:81], -1
	s_cmp_lg_u64 s[4:5], 0
	s_cbranch_scc1 .LBB0_319
	s_cmp_eq_u32 s99, 0
	s_cbranch_scc1 .Lq_fullA
	s_cmp_lg_u64 vcc, 0
	s_cbranch_scc1 .LBB0_319
	s_branch .Lq_fullA

.LBB0_321:
	s_add_i32 s12, s90, 3
	s_cmp_ge_i32 s12, s83
	s_cbranch_scc1 .Ldma_done
	s_cmp_eq_u32 s90, 0
	s_mov_b32 s13, s85
	s_cbranch_scc1 .Ldma_t
	s_cmp_lt_i32 s12, s82
	s_mov_b32 s13, s89
	s_cbranch_scc1 .Ldma_t
	s_add_i32 s13, s12, s84
.Ldma_t:
	s_mul_hi_i32 s81, s13, 0x30000
	s_mul_i32 s80, s13, 0x30000
	s_add_u32 s80, s60, s80
	s_addc_u32 s81, s61, s81
	v_lshl_add_u64 v[250:251], s[80:81], 0, v[0:1]
	v_lshl_add_u64 v[252:253], s[80:81], 0, v[170:171]
	s_add_i32 s12, s88, 0xc000
	s_and_b32 s12, s12, 0xffff
	s_add_i32 s12, s64, s12
	s_mov_b32 s13, m0
	s_mov_b32 m0, s12
	s_nop 0
	global_load_lds_dwordx4 v[250:251], off
	s_add_i32 s12, s12, 0x2000
	s_mov_b32 m0, s12
	s_nop 0
	global_load_lds_dwordx4 v[252:253], off
	s_mov_b32 m0, s13

.LBB0_777:
	v_and_b32_e32 v13, 15, v240
	v_and_b32_e32 v18, 48, v240
	v_mov_b32_e32 v83, v1
	s_and_b32 s56, s58, 3
	v_lshl_or_b32 v239, s12, 6, v13
	v_and_b32_e32 v12, 0xfffffc00, v12
	v_lshl_or_b32 v13, v13, 6, v18
	v_lshlrev_b32_e32 v18, 2, v240
	v_lshl_add_u64 v[14:15], s[76:77], 0, v[82:83]
	v_mov_b32_e32 v87, v1
	v_lshl_add_u32 v19, s12, 13, v12
	v_and_b32_e32 v18, 32, v18
	v_lshl_add_u32 v12, s56, 12, v12
	v_lshl_add_u64 v[16:17], s[76:77], 0, v[86:87]
	v_bitop3_b32 v19, v13, v19, v18 bitop3:0xde
	v_bitop3_b32 v108, v13, v12, v18 bitop3:0xde
	s_add_i32 m0, s57, 0x18000
	v_lshl_add_u64 v[12:13], v[14:15], 0, s[50:51]
	s_waitcnt vmcnt(2)
	s_barrier
	global_load_lds_dwordx4 v[12:13], off
	v_lshl_add_u64 v[12:13], v[16:17], 0, s[50:51]
	s_add_i32 m0, s57, 0x1a000
	s_add_i32 s68, s57, 0x8000
	global_load_lds_dwordx4 v[12:13], off
	v_lshl_add_u64 v[4:5], v[4:5], 0, s[50:51]
	s_mov_b32 m0, s68
	s_add_i32 s69, s57, 0xa000
	global_load_lds_dwordx4 v[4:5], off
	v_lshl_add_u64 v[2:3], v[2:3], 0, s[50:51]
	s_mov_b32 m0, s69
	s_xor_b64 s[82:83], s[92:93], -1
	global_load_lds_dwordx4 v[2:3], off
	s_add_i32 m0, s57, 0x1c000
	v_lshl_add_u64 v[2:3], s[80:81], 0, v[82:83]
	global_load_lds_dwordx4 v[2:3], off
	v_lshl_add_u64 v[2:3], s[80:81], 0, v[86:87]
	s_add_i32 m0, s57, 0x1e000
	v_readlane_b32 s55, v244, 7
	global_load_lds_dwordx4 v[2:3], off
	v_lshlrev_b32_e32 v2, 14, v6
	s_add_u32 s55, s90, s55
	v_readlane_b32 s90, v244, 8
	v_and_b32_e32 v2, 0xffff8000, v2
	s_addc_u32 s92, s91, s90
	s_lshl_b64 s[90:91], s[46:47], 25
	v_lshl_add_u32 v2, v7, 11, v2
	v_and_b32_e32 v3, 1, v6
	v_lshl_or_b32 v2, v3, 6, v2
	s_add_u32 s90, s55, s90
	v_lshl_add_u32 v2, v8, 1, v2
	v_mov_b32_e32 v3, v1
	s_addc_u32 s91, s92, s91
	v_lshl_add_u64 v[88:89], s[90:91], 0, v[2:3]
	v_lshlrev_b32_e32 v2, 14, v9
	v_and_b32_e32 v2, 0xffff8000, v2
	v_lshl_add_u32 v2, v10, 11, v2
	v_and_b32_e32 v3, 1, v9
	v_lshl_or_b32 v2, v3, 6, v2
	s_waitcnt vmcnt(6)
	v_lshl_add_u32 v2, v11, 1, v2
	v_mov_b32_e32 v3, v1
	v_lshl_add_u64 v[106:107], s[90:91], 0, v[2:3]
	s_mov_b32 vcc_lo, -2
	s_mov_b64 s[90:91], 0
	v_add_u32_e32 v109, 0, v19
	s_barrier
	v_add_u32_e32 v154, s63, v108
	v_add_u32_e32 v170, s10, v108
	s_add_u32 s92, s90, 0x100
	ds_read_b128 v[110:113], v154
	ds_read_b128 v[146:149], v154 offset:1024
	ds_read_b128 v[150:153], v154 offset:2048
	ds_read_b128 v[154:157], v154 offset:3072
	ds_read_b128 v[158:161], v170
	ds_read_b128 v[162:165], v170 offset:1024
	ds_read_b128 v[166:169], v170 offset:2048
	ds_read_b128 v[170:173], v170 offset:3072
	s_addc_u32 s93, s91, 0
	s_cmp_lg_u32 vcc_lo, 12
	s_cselect_b32 s94, s92, 0
	s_cselect_b32 s55, s93, 0
	s_add_u32 s96, s88, s94
	s_addc_u32 s97, s89, s55
	s_add_u32 s94, s76, s94
	s_addc_u32 s95, s77, s55
	v_lshl_add_u64 v[208:209], v[88:89], 0, s[90:91]
	s_add_i32 m0, s57, 0xc000
	ds_read_b128 v[174:177], v109
	ds_read_b128 v[178:181], v109 offset:1024
	ds_read_b128 v[182:185], v109 offset:2048
	ds_read_b128 v[186:189], v109 offset:3072
	ds_read_b128 v[192:195], v109 offset:4096
	ds_read_b128 v[196:199], v109 offset:5120
	ds_read_b128 v[200:203], v109 offset:6144
	ds_read_b128 v[204:207], v109 offset:7168
	global_load_lds_dwordx4 v[208:209], off
	v_lshl_add_u64 v[208:209], v[106:107], 0, s[90:91]
	s_add_i32 m0, s57, 0xe000
	s_nop 0
	global_load_lds_dwordx4 v[208:209], off
	s_waitcnt vmcnt(8)
	s_waitcnt lgkmcnt(0)
	s_barrier
	s_setprio 1
	s_waitcnt lgkmcnt(0)
	v_mfma_f32_16x16x32_bf16 v[126:129], v[110:113], v[174:177], 0
	v_mfma_f32_16x16x32_bf16 v[118:121], v[150:153], v[174:177], 0
	v_mfma_f32_16x16x32_bf16 v[138:141], v[110:113], v[182:185], 0
	v_mfma_f32_16x16x32_bf16 v[134:137], v[150:153], v[182:185], 0
	v_mfma_f32_16x16x32_bf16 v[102:105], v[110:113], v[192:195], 0
	v_mfma_f32_16x16x32_bf16 v[98:101], v[150:153], v[192:195], 0
	v_mfma_f32_16x16x32_bf16 v[78:81], v[110:113], v[200:203], 0
	v_mfma_f32_16x16x32_bf16 v[74:77], v[150:153], v[200:203], 0
	v_mfma_f32_16x16x32_bf16 v[126:129], v[146:149], v[178:181], v[126:129]
	v_mfma_f32_16x16x32_bf16 v[118:121], v[154:157], v[178:181], v[118:121]
	v_mfma_f32_16x16x32_bf16 v[138:141], v[146:149], v[186:189], v[138:141]
	v_mfma_f32_16x16x32_bf16 v[134:137], v[154:157], v[186:189], v[134:137]
	v_mfma_f32_16x16x32_bf16 v[102:105], v[146:149], v[196:199], v[102:105]
	v_mfma_f32_16x16x32_bf16 v[98:101], v[154:157], v[196:199], v[98:101]
	v_mfma_f32_16x16x32_bf16 v[78:81], v[146:149], v[204:207], v[78:81]
	v_mfma_f32_16x16x32_bf16 v[74:77], v[154:157], v[204:207], v[74:77]
	s_setprio 0
	s_setprio 1
	v_mfma_f32_16x16x32_bf16 v[142:145], v[158:161], v[174:177], 0
	v_mfma_f32_16x16x32_bf16 v[114:117], v[166:169], v[174:177], 0
	v_mfma_f32_16x16x32_bf16 v[130:133], v[158:161], v[182:185], 0
	v_mfma_f32_16x16x32_bf16 v[122:125], v[166:169], v[182:185], 0
	v_mfma_f32_16x16x32_bf16 v[94:97], v[158:161], v[192:195], 0
	v_mfma_f32_16x16x32_bf16 v[90:93], v[166:169], v[192:195], 0
	v_mfma_f32_16x16x32_bf16 v[70:73], v[158:161], v[200:203], 0
	v_mfma_f32_16x16x32_bf16 v[66:69], v[166:169], v[200:203], 0
	v_mfma_f32_16x16x32_bf16 v[142:145], v[162:165], v[178:181], v[142:145]
	v_mfma_f32_16x16x32_bf16 v[114:117], v[170:173], v[178:181], v[114:117]
	v_mfma_f32_16x16x32_bf16 v[130:133], v[162:165], v[186:189], v[130:133]
	v_mfma_f32_16x16x32_bf16 v[122:125], v[170:173], v[186:189], v[122:125]
	v_mfma_f32_16x16x32_bf16 v[94:97], v[162:165], v[196:199], v[94:97]
	v_mfma_f32_16x16x32_bf16 v[90:93], v[170:173], v[196:199], v[90:93]
	v_mfma_f32_16x16x32_bf16 v[70:73], v[162:165], v[204:207], v[70:73]
	v_mfma_f32_16x16x32_bf16 v[66:69], v[170:173], v[204:207], v[66:69]
	s_setprio 0
	s_barrier
	s_add_i32 s55, s63, s13
	v_lshl_add_u64 v[208:209], s[94:95], 0, v[82:83]
	s_mov_b32 m0, s55
	ds_read_b128 v[174:177], v109 offset:16384
	ds_read_b128 v[178:181], v109 offset:17408
	ds_read_b128 v[182:185], v109 offset:18432
	ds_read_b128 v[186:189], v109 offset:19456
	ds_read_b128 v[192:195], v109 offset:20480
	ds_read_b128 v[196:199], v109 offset:21504
	ds_read_b128 v[200:203], v109 offset:22528
	ds_read_b128 v[204:207], v109 offset:23552
	global_load_lds_dwordx4 v[208:209], off
	s_add_i32 m0, s55, 0x2000
	s_add_u32 s90, s94, 0x40000
	v_lshl_add_u64 v[210:211], s[94:95], 0, v[86:87]
	s_addc_u32 s91, s95, 0
	s_add_i32 s55, s10, s13
	global_load_lds_dwordx4 v[210:211], off
	v_lshl_add_u64 v[212:213], s[90:91], 0, v[82:83]
	s_mov_b32 m0, s55
	v_lshl_add_u64 v[214:215], s[96:97], 0, v[84:85]
	global_load_lds_dwordx4 v[212:213], off
	v_lshl_add_u64 v[212:213], s[90:91], 0, v[86:87]
	s_add_i32 m0, s55, 0x2000
	s_nop 0
	global_load_lds_dwordx4 v[212:213], off
	v_lshl_add_u64 v[212:213], s[96:97], 0, v[0:1]
	s_mov_b32 m0, s57
	s_nop 0
	global_load_lds_dwordx4 v[212:213], off
	s_mov_b32 m0, s59
	s_nop 0
	global_load_lds_dwordx4 v[214:215], off
	s_waitcnt vmcnt(8)
	s_waitcnt lgkmcnt(0)
	s_barrier
	s_setprio 1
	s_waitcnt lgkmcnt(0)
	v_mfma_f32_16x16x32_bf16 v[62:65], v[110:113], v[174:177], 0
	v_mfma_f32_16x16x32_bf16 v[58:61], v[150:153], v[174:177], 0
	v_mfma_f32_16x16x32_bf16 v[46:49], v[110:113], v[182:185], 0
	v_mfma_f32_16x16x32_bf16 v[42:45], v[150:153], v[182:185], 0
	v_mfma_f32_16x16x32_bf16 v[30:33], v[110:113], v[192:195], 0
	v_mfma_f32_16x16x32_bf16 v[26:29], v[150:153], v[192:195], 0
	v_mfma_f32_16x16x32_bf16 v[14:17], v[110:113], v[200:203], 0
	v_mfma_f32_16x16x32_bf16 v[10:13], v[150:153], v[200:203], 0
	v_mfma_f32_16x16x32_bf16 v[62:65], v[146:149], v[178:181], v[62:65]
	v_mfma_f32_16x16x32_bf16 v[58:61], v[154:157], v[178:181], v[58:61]
	v_mfma_f32_16x16x32_bf16 v[46:49], v[146:149], v[186:189], v[46:49]
	v_mfma_f32_16x16x32_bf16 v[42:45], v[154:157], v[186:189], v[42:45]
	v_mfma_f32_16x16x32_bf16 v[30:33], v[146:149], v[196:199], v[30:33]
	v_mfma_f32_16x16x32_bf16 v[26:29], v[154:157], v[196:199], v[26:29]
	v_mfma_f32_16x16x32_bf16 v[14:17], v[146:149], v[204:207], v[14:17]
	v_mfma_f32_16x16x32_bf16 v[10:13], v[154:157], v[204:207], v[10:13]
	s_setprio 0
	s_setprio 1
	v_mfma_f32_16x16x32_bf16 v[54:57], v[158:161], v[174:177], 0
	v_mfma_f32_16x16x32_bf16 v[50:53], v[166:169], v[174:177], 0
	v_mfma_f32_16x16x32_bf16 v[38:41], v[158:161], v[182:185], 0
	v_mfma_f32_16x16x32_bf16 v[34:37], v[166:169], v[182:185], 0
	v_mfma_f32_16x16x32_bf16 v[22:25], v[158:161], v[192:195], 0
	v_mfma_f32_16x16x32_bf16 v[18:21], v[166:169], v[192:195], 0
	v_mfma_f32_16x16x32_bf16 v[6:9], v[158:161], v[200:203], 0
	v_mfma_f32_16x16x32_bf16 v[2:5], v[166:169], v[200:203], 0
	v_mfma_f32_16x16x32_bf16 v[54:57], v[162:165], v[178:181], v[54:57]
	v_mfma_f32_16x16x32_bf16 v[50:53], v[170:173], v[178:181], v[50:53]
	v_mfma_f32_16x16x32_bf16 v[38:41], v[162:165], v[186:189], v[38:41]
	v_mfma_f32_16x16x32_bf16 v[34:37], v[170:173], v[186:189], v[34:37]
	v_mfma_f32_16x16x32_bf16 v[22:25], v[162:165], v[196:199], v[22:25]
	v_mfma_f32_16x16x32_bf16 v[18:21], v[170:173], v[196:199], v[18:21]
	v_mfma_f32_16x16x32_bf16 v[6:9], v[162:165], v[204:207], v[6:9]
	v_mfma_f32_16x16x32_bf16 v[2:5], v[170:173], v[204:207], v[2:5]
	s_setprio 0
	s_barrier
	v_add_u32_e32 v154, s11, v108
	v_add_u32_e32 v170, s67, v108
	ds_read_b128 v[110:113], v154
	ds_read_b128 v[146:149], v154 offset:1024
	ds_read_b128 v[150:153], v154 offset:2048
	ds_read_b128 v[154:157], v154 offset:3072
	ds_read_b128 v[158:161], v170
	ds_read_b128 v[162:165], v170 offset:1024
	ds_read_b128 v[166:169], v170 offset:2048
	ds_read_b128 v[170:173], v170 offset:3072
	s_add_u32 s90, s96, 0x40000
	s_addc_u32 s91, s97, 0
	s_mov_b32 m0, s60
	v_lshl_add_u64 v[216:217], s[90:91], 0, v[0:1]
	ds_read_b128 v[174:177], v109 offset:32768
	ds_read_b128 v[178:181], v109 offset:33792
	ds_read_b128 v[182:185], v109 offset:34816
	ds_read_b128 v[186:189], v109 offset:35840
	ds_read_b128 v[192:195], v109 offset:36864
	ds_read_b128 v[196:199], v109 offset:37888
	ds_read_b128 v[200:203], v109 offset:38912
	ds_read_b128 v[204:207], v109 offset:39936
	global_load_lds_dwordx4 v[216:217], off
	v_lshl_add_u64 v[216:217], s[90:91], 0, v[84:85]
	s_mov_b32 m0, s61
	s_nop 0
	global_load_lds_dwordx4 v[216:217], off
	s_waitcnt vmcnt(8)
	s_waitcnt lgkmcnt(0)
	s_barrier
	s_setprio 1
	s_waitcnt lgkmcnt(0)
	v_mfma_f32_16x16x32_bf16 v[126:129], v[110:113], v[174:177], v[126:129]
	v_mfma_f32_16x16x32_bf16 v[118:121], v[150:153], v[174:177], v[118:121]
	v_mfma_f32_16x16x32_bf16 v[138:141], v[110:113], v[182:185], v[138:141]
	v_mfma_f32_16x16x32_bf16 v[134:137], v[150:153], v[182:185], v[134:137]
	v_mfma_f32_16x16x32_bf16 v[102:105], v[110:113], v[192:195], v[102:105]
	v_mfma_f32_16x16x32_bf16 v[98:101], v[150:153], v[192:195], v[98:101]
	v_mfma_f32_16x16x32_bf16 v[78:81], v[110:113], v[200:203], v[78:81]
	v_mfma_f32_16x16x32_bf16 v[74:77], v[150:153], v[200:203], v[74:77]
	v_mfma_f32_16x16x32_bf16 v[126:129], v[146:149], v[178:181], v[126:129]
	v_mfma_f32_16x16x32_bf16 v[118:121], v[154:157], v[178:181], v[118:121]
	v_mfma_f32_16x16x32_bf16 v[138:141], v[146:149], v[186:189], v[138:141]
	v_mfma_f32_16x16x32_bf16 v[134:137], v[154:157], v[186:189], v[134:137]
	v_mfma_f32_16x16x32_bf16 v[102:105], v[146:149], v[196:199], v[102:105]
	v_mfma_f32_16x16x32_bf16 v[98:101], v[154:157], v[196:199], v[98:101]
	v_mfma_f32_16x16x32_bf16 v[78:81], v[146:149], v[204:207], v[78:81]
	v_mfma_f32_16x16x32_bf16 v[74:77], v[154:157], v[204:207], v[74:77]
	s_setprio 0
	s_setprio 1
	v_mfma_f32_16x16x32_bf16 v[142:145], v[158:161], v[174:177], v[142:145]
	v_mfma_f32_16x16x32_bf16 v[114:117], v[166:169], v[174:177], v[114:117]
	v_mfma_f32_16x16x32_bf16 v[130:133], v[158:161], v[182:185], v[130:133]
	v_mfma_f32_16x16x32_bf16 v[122:125], v[166:169], v[182:185], v[122:125]
	v_mfma_f32_16x16x32_bf16 v[94:97], v[158:161], v[192:195], v[94:97]
	v_mfma_f32_16x16x32_bf16 v[90:93], v[166:169], v[192:195], v[90:93]
	v_mfma_f32_16x16x32_bf16 v[70:73], v[158:161], v[200:203], v[70:73]
	v_mfma_f32_16x16x32_bf16 v[66:69], v[166:169], v[200:203], v[66:69]
	v_mfma_f32_16x16x32_bf16 v[142:145], v[162:165], v[178:181], v[142:145]
	v_mfma_f32_16x16x32_bf16 v[114:117], v[170:173], v[178:181], v[114:117]
	v_mfma_f32_16x16x32_bf16 v[130:133], v[162:165], v[186:189], v[130:133]
	v_mfma_f32_16x16x32_bf16 v[122:125], v[170:173], v[186:189], v[122:125]
	v_mfma_f32_16x16x32_bf16 v[94:97], v[162:165], v[196:199], v[94:97]
	v_mfma_f32_16x16x32_bf16 v[90:93], v[170:173], v[196:199], v[90:93]
	v_mfma_f32_16x16x32_bf16 v[70:73], v[162:165], v[204:207], v[70:73]
	v_mfma_f32_16x16x32_bf16 v[66:69], v[170:173], v[204:207], v[66:69]
	s_setprio 0
	s_barrier
	s_add_i32 s55, s11, s13
	v_lshl_add_u64 v[208:209], v[208:209], 0, s[50:51]
	s_mov_b32 m0, s55
	ds_read_b128 v[174:177], v109 offset:49152
	ds_read_b128 v[178:181], v109 offset:50176
	ds_read_b128 v[182:185], v109 offset:51200
	ds_read_b128 v[186:189], v109 offset:52224
	ds_read_b128 v[192:195], v109 offset:53248
	ds_read_b128 v[196:199], v109 offset:54272
	ds_read_b128 v[200:203], v109 offset:55296
	ds_read_b128 v[204:207], v109 offset:56320
	global_load_lds_dwordx4 v[208:209], off
	s_add_i32 m0, s55, 0x2000
	s_add_u32 s90, s94, 0x40080
	v_lshl_add_u64 v[208:209], v[210:211], 0, s[50:51]
	s_addc_u32 s91, s95, 0
	s_add_i32 s55, s67, s13
	global_load_lds_dwordx4 v[208:209], off
	v_lshl_add_u64 v[208:209], s[90:91], 0, v[82:83]
	s_mov_b32 m0, s55
	s_nop 0
	global_load_lds_dwordx4 v[208:209], off
	v_lshl_add_u64 v[208:209], s[90:91], 0, v[86:87]
	s_add_i32 m0, s55, 0x2000
	s_nop 0
	global_load_lds_dwordx4 v[208:209], off
	v_lshl_add_u64 v[208:209], v[212:213], 0, s[50:51]
	s_mov_b32 m0, s68
	s_nop 0
	global_load_lds_dwordx4 v[208:209], off
	v_lshl_add_u64 v[208:209], v[214:215], 0, s[50:51]
	s_mov_b32 m0, s69
	s_nop 0
	global_load_lds_dwordx4 v[208:209], off
	s_waitcnt vmcnt(8)
	s_waitcnt lgkmcnt(0)
	s_barrier
	s_setprio 1
	s_waitcnt lgkmcnt(0)
	v_mfma_f32_16x16x32_bf16 v[62:65], v[110:113], v[174:177], v[62:65]
	v_mfma_f32_16x16x32_bf16 v[58:61], v[150:153], v[174:177], v[58:61]
	v_mfma_f32_16x16x32_bf16 v[46:49], v[110:113], v[182:185], v[46:49]
	v_mfma_f32_16x16x32_bf16 v[42:45], v[150:153], v[182:185], v[42:45]
	v_mfma_f32_16x16x32_bf16 v[30:33], v[110:113], v[192:195], v[30:33]
	v_mfma_f32_16x16x32_bf16 v[26:29], v[150:153], v[192:195], v[26:29]
	v_mfma_f32_16x16x32_bf16 v[14:17], v[110:113], v[200:203], v[14:17]
	v_mfma_f32_16x16x32_bf16 v[10:13], v[150:153], v[200:203], v[10:13]
	v_mfma_f32_16x16x32_bf16 v[62:65], v[146:149], v[178:181], v[62:65]
	v_mfma_f32_16x16x32_bf16 v[58:61], v[154:157], v[178:181], v[58:61]
	v_mfma_f32_16x16x32_bf16 v[46:49], v[146:149], v[186:189], v[46:49]
	v_mfma_f32_16x16x32_bf16 v[42:45], v[154:157], v[186:189], v[42:45]
	v_mfma_f32_16x16x32_bf16 v[30:33], v[146:149], v[196:199], v[30:33]
	v_mfma_f32_16x16x32_bf16 v[26:29], v[154:157], v[196:199], v[26:29]
	v_mfma_f32_16x16x32_bf16 v[14:17], v[146:149], v[204:207], v[14:17]
	v_mfma_f32_16x16x32_bf16 v[10:13], v[154:157], v[204:207], v[10:13]
	s_setprio 0
	s_setprio 1
	v_mfma_f32_16x16x32_bf16 v[54:57], v[158:161], v[174:177], v[54:57]
	v_mfma_f32_16x16x32_bf16 v[50:53], v[166:169], v[174:177], v[50:53]
	v_mfma_f32_16x16x32_bf16 v[38:41], v[158:161], v[182:185], v[38:41]
	v_mfma_f32_16x16x32_bf16 v[34:37], v[166:169], v[182:185], v[34:37]
	v_mfma_f32_16x16x32_bf16 v[22:25], v[158:161], v[192:195], v[22:25]
	v_mfma_f32_16x16x32_bf16 v[18:21], v[166:169], v[192:195], v[18:21]
	v_mfma_f32_16x16x32_bf16 v[6:9], v[158:161], v[200:203], v[6:9]
	v_mfma_f32_16x16x32_bf16 v[2:5], v[166:169], v[200:203], v[2:5]
	v_mfma_f32_16x16x32_bf16 v[54:57], v[162:165], v[178:181], v[54:57]
	v_mfma_f32_16x16x32_bf16 v[50:53], v[170:173], v[178:181], v[50:53]
	v_mfma_f32_16x16x32_bf16 v[38:41], v[162:165], v[186:189], v[38:41]
	v_mfma_f32_16x16x32_bf16 v[34:37], v[170:173], v[186:189], v[34:37]
	v_mfma_f32_16x16x32_bf16 v[22:25], v[162:165], v[196:199], v[22:25]
	v_mfma_f32_16x16x32_bf16 v[18:21], v[170:173], v[196:199], v[18:21]
	v_mfma_f32_16x16x32_bf16 v[6:9], v[162:165], v[204:207], v[6:9]
	v_mfma_f32_16x16x32_bf16 v[2:5], v[170:173], v[204:207], v[2:5]
	s_setprio 0
	s_barrier
	s_add_i32 vcc_lo, vcc_lo, 2
	s_mov_b64 s[90:91], s[92:93]
